# layer-1 weight-conversion items spread more evenly over the PAB / L0 up2 / L1 up1 partial-round slots (on top of flat release)
# speedup vs baseline: 1.0147x; 1.0147x over previous
; #define LAS __attribute__((address_space(3)))
; __device__ __forceinline__ void prologue(const kptr_t kp, LAS float* scr, int gw, int NGW, int lane) {
;     unsigned char* ws = KPTR(unsigned char, 23);
;     for (int it = gw; it < IT_TOTAL; it += NGW) {
;         int r = it;
.LBB0_1054:
	s_cmp_lt_u32 s2, 16
	s_cbranch_scc1 .Lslot_3_skip
	v_writelane_b32 v250, s3, 0
	v_writelane_b32 v250, s4, 1
	v_writelane_b32 v250, s5, 2
	v_writelane_b32 v250, s6, 3
	v_writelane_b32 v250, s7, 4
	v_writelane_b32 v250, s8, 5
	v_writelane_b32 v250, s9, 6
	v_writelane_b32 v250, s10, 7
	v_writelane_b32 v250, s11, 8
	v_writelane_b32 v250, s12, 9
	v_writelane_b32 v250, s13, 10
	v_writelane_b32 v250, s14, 11
	v_writelane_b32 v250, s15, 12
	v_writelane_b32 v250, s16, 13
	v_writelane_b32 v250, s17, 14
	v_writelane_b32 v250, s18, 15
	v_writelane_b32 v250, s19, 16
	v_writelane_b32 v250, s20, 17
	v_writelane_b32 v250, s21, 18
	v_writelane_b32 v250, s22, 19
	v_writelane_b32 v250, s23, 20
	v_writelane_b32 v250, s24, 21
	v_writelane_b32 v250, s25, 22
	v_writelane_b32 v250, s26, 23
	v_writelane_b32 v250, s27, 24
	v_writelane_b32 v250, s28, 25
	v_writelane_b32 v250, s29, 26
	v_writelane_b32 v250, s30, 27
	v_writelane_b32 v250, s31, 28
	v_writelane_b32 v250, s32, 29
	v_writelane_b32 v250, s33, 30
	v_writelane_b32 v250, s34, 31
	v_writelane_b32 v250, s35, 32
	v_writelane_b32 v250, s36, 33
	v_writelane_b32 v250, s37, 34
	v_writelane_b32 v250, s38, 35
	v_writelane_b32 v250, s39, 36
	v_writelane_b32 v250, s40, 37
	v_writelane_b32 v250, s41, 38
	v_writelane_b32 v250, s42, 39
	v_writelane_b32 v250, s43, 40
	v_writelane_b32 v250, s44, 41
	v_writelane_b32 v250, s45, 42
	v_writelane_b32 v250, s46, 43
	v_writelane_b32 v250, s47, 44
	v_writelane_b32 v250, s48, 45
	v_writelane_b32 v250, s49, 46
	v_writelane_b32 v250, s50, 47
	v_writelane_b32 v250, s51, 48
	v_writelane_b32 v250, s52, 49
	v_writelane_b32 v250, s53, 50
	v_writelane_b32 v250, s54, 51
	v_writelane_b32 v250, s55, 52
	v_writelane_b32 v250, s56, 53
	v_writelane_b32 v250, s57, 54
	v_writelane_b32 v250, s58, 55
	v_writelane_b32 v250, s59, 56
	v_writelane_b32 v250, s60, 57
	v_writelane_b32 v250, s61, 58
	v_writelane_b32 v250, s62, 59
	v_writelane_b32 v250, s63, 60
	v_writelane_b32 v250, s64, 61
	v_writelane_b32 v250, s65, 62
	v_writelane_b32 v250, s66, 63
	v_writelane_b32 v251, s67, 0
	v_writelane_b32 v251, s68, 1
	v_writelane_b32 v251, s69, 2
	v_writelane_b32 v251, s70, 3
	v_writelane_b32 v251, s71, 4
	v_writelane_b32 v251, s72, 5
	v_writelane_b32 v251, s73, 6
	v_writelane_b32 v251, s74, 7
	v_writelane_b32 v251, s75, 8
	v_writelane_b32 v251, s76, 9
	v_writelane_b32 v251, s77, 10
	v_writelane_b32 v251, s78, 11
	v_writelane_b32 v251, s79, 12
	v_writelane_b32 v251, s80, 13
	v_writelane_b32 v251, s81, 14
	v_writelane_b32 v251, s82, 15
	v_writelane_b32 v251, s83, 16
	v_writelane_b32 v251, s84, 17
	v_writelane_b32 v251, s85, 18
	v_writelane_b32 v251, s86, 19
	v_writelane_b32 v251, s87, 20
	v_writelane_b32 v251, s88, 21
	v_writelane_b32 v251, s89, 22
	v_writelane_b32 v251, s90, 23
	v_writelane_b32 v251, s91, 24
	v_writelane_b32 v251, s92, 25
	v_writelane_b32 v251, s93, 26
	v_writelane_b32 v251, s94, 27
	v_writelane_b32 v251, s95, 28
	v_writelane_b32 v251, s96, 29
	v_writelane_b32 v251, s97, 30
	v_mov_b32_e32 v236, v200
	v_mov_b32_e32 v237, v201
	v_mov_b32_e32 v238, v202
	v_mov_b32_e32 v239, v203
	v_mov_b32_e32 v240, v204
	v_mov_b32_e32 v241, v205
	v_mov_b32_e32 v242, v206
	v_mov_b32_e32 v243, v207
	v_mov_b32_e32 v244, v208
	v_mov_b32_e32 v245, v209
	v_mov_b32_e32 v246, v210
	v_mov_b32_e32 v247, v211
	s_mov_b32 s98, 0x3a80
	s_mov_b32 s99, 0x780
	s_mov_b32 s100, 0x4600
	s_mov_b32 s101, 13
	s_branch .Lcv_hop2
.Lslot_3_ret:
	s_cmp_eq_u32 s100, 0x4600
	s_cbranch_scc0 .Lslot_3_done
	s_mov_b32 s98, 0x1c0
	s_mov_b32 s100, 0x480
	s_branch .Lcv_hop2

; #define LAS __attribute__((address_space(3)))
; __device__ __forceinline__ void prologue(const kptr_t kp, LAS float* scr, int gw, int NGW, int lane) {
;     unsigned char* ws = KPTR(unsigned char, 23);
;     for (int it = gw; it < IT_TOTAL; it += NGW) {
;         int r = it;
.LBB0_1270:
	s_cmp_lt_u32 s2, 44
	s_cbranch_scc1 .Lslot_4_skip
	v_writelane_b32 v250, s3, 0
	v_writelane_b32 v250, s4, 1
	v_writelane_b32 v250, s5, 2
	v_writelane_b32 v250, s6, 3
	v_writelane_b32 v250, s7, 4
	v_writelane_b32 v250, s8, 5
	v_writelane_b32 v250, s9, 6
	v_writelane_b32 v250, s10, 7
	v_writelane_b32 v250, s11, 8
	v_writelane_b32 v250, s12, 9
	v_writelane_b32 v250, s13, 10
	v_writelane_b32 v250, s14, 11
	v_writelane_b32 v250, s15, 12
	v_writelane_b32 v250, s16, 13
	v_writelane_b32 v250, s17, 14
	v_writelane_b32 v250, s18, 15
	v_writelane_b32 v250, s19, 16
	v_writelane_b32 v250, s20, 17
	v_writelane_b32 v250, s21, 18
	v_writelane_b32 v250, s22, 19
	v_writelane_b32 v250, s23, 20
	v_writelane_b32 v250, s24, 21
	v_writelane_b32 v250, s25, 22
	v_writelane_b32 v250, s26, 23
	v_writelane_b32 v250, s27, 24
	v_writelane_b32 v250, s28, 25
	v_writelane_b32 v250, s29, 26
	v_writelane_b32 v250, s30, 27
	v_writelane_b32 v250, s31, 28
	v_writelane_b32 v250, s32, 29
	v_writelane_b32 v250, s33, 30
	v_writelane_b32 v250, s34, 31
	v_writelane_b32 v250, s35, 32
	v_writelane_b32 v250, s36, 33
	v_writelane_b32 v250, s37, 34
	v_writelane_b32 v250, s38, 35
	v_writelane_b32 v250, s39, 36
	v_writelane_b32 v250, s40, 37
	v_writelane_b32 v250, s41, 38
	v_writelane_b32 v250, s42, 39
	v_writelane_b32 v250, s43, 40
	v_writelane_b32 v250, s44, 41
	v_writelane_b32 v250, s45, 42
	v_writelane_b32 v250, s46, 43
	v_writelane_b32 v250, s47, 44
	v_writelane_b32 v250, s48, 45
	v_writelane_b32 v250, s49, 46
	v_writelane_b32 v250, s50, 47
	v_writelane_b32 v250, s51, 48
	v_writelane_b32 v250, s52, 49
	v_writelane_b32 v250, s53, 50
	v_writelane_b32 v250, s54, 51
	v_writelane_b32 v250, s55, 52
	v_writelane_b32 v250, s56, 53
	v_writelane_b32 v250, s57, 54
	v_writelane_b32 v250, s58, 55
	v_writelane_b32 v250, s59, 56
	v_writelane_b32 v250, s60, 57
	v_writelane_b32 v250, s61, 58
	v_writelane_b32 v250, s62, 59
	v_writelane_b32 v250, s63, 60
	v_writelane_b32 v250, s64, 61
	v_writelane_b32 v250, s65, 62
	v_writelane_b32 v250, s66, 63
	v_writelane_b32 v251, s67, 0
	v_writelane_b32 v251, s68, 1
	v_writelane_b32 v251, s69, 2
	v_writelane_b32 v251, s70, 3
	v_writelane_b32 v251, s71, 4
	v_writelane_b32 v251, s72, 5
	v_writelane_b32 v251, s73, 6
	v_writelane_b32 v251, s74, 7
	v_writelane_b32 v251, s75, 8
	v_writelane_b32 v251, s76, 9
	v_writelane_b32 v251, s77, 10
	v_writelane_b32 v251, s78, 11
	v_writelane_b32 v251, s79, 12
	v_writelane_b32 v251, s80, 13
	v_writelane_b32 v251, s81, 14
	v_writelane_b32 v251, s82, 15
	v_writelane_b32 v251, s83, 16
	v_writelane_b32 v251, s84, 17
	v_writelane_b32 v251, s85, 18
	v_writelane_b32 v251, s86, 19
	v_writelane_b32 v251, s87, 20
	v_writelane_b32 v251, s88, 21
	v_writelane_b32 v251, s89, 22
	v_writelane_b32 v251, s90, 23
	v_writelane_b32 v251, s91, 24
	v_writelane_b32 v251, s92, 25
	v_writelane_b32 v251, s93, 26
	v_writelane_b32 v251, s94, 27
	v_writelane_b32 v251, s95, 28
	v_writelane_b32 v251, s96, 29
	v_writelane_b32 v251, s97, 30
	v_mov_b32_e32 v236, v200
	v_mov_b32_e32 v237, v201
	v_mov_b32_e32 v238, v202
	v_mov_b32_e32 v239, v203
	v_mov_b32_e32 v240, v204
	v_mov_b32_e32 v241, v205
	v_mov_b32_e32 v242, v206
	v_mov_b32_e32 v243, v207
	v_mov_b32_e32 v244, v208
	v_mov_b32_e32 v245, v209
	v_mov_b32_e32 v246, v210
	v_mov_b32_e32 v247, v211
	s_mov_b32 s98, 0x44a0
	s_mov_b32 s99, 0x6a0
	s_mov_b32 s100, 0x5480
	s_mov_b32 s101, 14
	s_branch .Lcv_hop2

; #define LAS __attribute__((address_space(3)))
; __device__ __forceinline__ void prologue(const kptr_t kp, LAS float* scr, int gw, int NGW, int lane) {
;     unsigned char* ws = KPTR(unsigned char, 23);
;     for (int it = gw; it < IT_TOTAL; it += NGW) {
;         int r = it;
.LBB0_1490:
	s_cmp_lt_u32 s2, 44
	s_cbranch_scc1 .Lslot_5_skip
	v_writelane_b32 v250, s3, 0
	v_writelane_b32 v250, s4, 1
	v_writelane_b32 v250, s5, 2
	v_writelane_b32 v250, s6, 3
	v_writelane_b32 v250, s7, 4
	v_writelane_b32 v250, s8, 5
	v_writelane_b32 v250, s9, 6
	v_writelane_b32 v250, s10, 7
	v_writelane_b32 v250, s11, 8
	v_writelane_b32 v250, s12, 9
	v_writelane_b32 v250, s13, 10
	v_writelane_b32 v250, s14, 11
	v_writelane_b32 v250, s15, 12
	v_writelane_b32 v250, s16, 13
	v_writelane_b32 v250, s17, 14
	v_writelane_b32 v250, s18, 15
	v_writelane_b32 v250, s19, 16
	v_writelane_b32 v250, s20, 17
	v_writelane_b32 v250, s21, 18
	v_writelane_b32 v250, s22, 19
	v_writelane_b32 v250, s23, 20
	v_writelane_b32 v250, s24, 21
	v_writelane_b32 v250, s25, 22
	v_writelane_b32 v250, s26, 23
	v_writelane_b32 v250, s27, 24
	v_writelane_b32 v250, s28, 25
	v_writelane_b32 v250, s29, 26
	v_writelane_b32 v250, s30, 27
	v_writelane_b32 v250, s31, 28
	v_writelane_b32 v250, s32, 29
	v_writelane_b32 v250, s33, 30
	v_writelane_b32 v250, s34, 31
	v_writelane_b32 v250, s35, 32
	v_writelane_b32 v250, s36, 33
	v_writelane_b32 v250, s37, 34
	v_writelane_b32 v250, s38, 35
	v_writelane_b32 v250, s39, 36
	v_writelane_b32 v250, s40, 37
	v_writelane_b32 v250, s41, 38
	v_writelane_b32 v250, s42, 39
	v_writelane_b32 v250, s43, 40
	v_writelane_b32 v250, s44, 41
	v_writelane_b32 v250, s45, 42
	v_writelane_b32 v250, s46, 43
	v_writelane_b32 v250, s47, 44
	v_writelane_b32 v250, s48, 45
	v_writelane_b32 v250, s49, 46
	v_writelane_b32 v250, s50, 47
	v_writelane_b32 v250, s51, 48
	v_writelane_b32 v250, s52, 49
	v_writelane_b32 v250, s53, 50
	v_writelane_b32 v250, s54, 51
	v_writelane_b32 v250, s55, 52
	v_writelane_b32 v250, s56, 53
	v_writelane_b32 v250, s57, 54
	v_writelane_b32 v250, s58, 55
	v_writelane_b32 v250, s59, 56
	v_writelane_b32 v250, s60, 57
	v_writelane_b32 v250, s61, 58
	v_writelane_b32 v250, s62, 59
	v_writelane_b32 v250, s63, 60
	v_writelane_b32 v250, s64, 61
	v_writelane_b32 v250, s65, 62
	v_writelane_b32 v250, s66, 63
	v_writelane_b32 v251, s67, 0
	v_writelane_b32 v251, s68, 1
	v_writelane_b32 v251, s69, 2
	v_writelane_b32 v251, s70, 3
	v_writelane_b32 v251, s71, 4
	v_writelane_b32 v251, s72, 5
	v_writelane_b32 v251, s73, 6
	v_writelane_b32 v251, s74, 7
	v_writelane_b32 v251, s75, 8
	v_writelane_b32 v251, s76, 9
	v_writelane_b32 v251, s77, 10
	v_writelane_b32 v251, s78, 11
	v_writelane_b32 v251, s79, 12
	v_writelane_b32 v251, s80, 13
	v_writelane_b32 v251, s81, 14
	v_writelane_b32 v251, s82, 15
	v_writelane_b32 v251, s83, 16
	v_writelane_b32 v251, s84, 17
	v_writelane_b32 v251, s85, 18
	v_writelane_b32 v251, s86, 19
	v_writelane_b32 v251, s87, 20
	v_writelane_b32 v251, s88, 21
	v_writelane_b32 v251, s89, 22
	v_writelane_b32 v251, s90, 23
	v_writelane_b32 v251, s91, 24
	v_writelane_b32 v251, s92, 25
	v_writelane_b32 v251, s93, 26
	v_writelane_b32 v251, s94, 27
	v_writelane_b32 v251, s95, 28
	v_writelane_b32 v251, s96, 29
	v_writelane_b32 v251, s97, 30
	v_mov_b32_e32 v236, v200
	v_mov_b32_e32 v237, v201
	v_mov_b32_e32 v238, v202
	v_mov_b32_e32 v239, v203
	v_mov_b32_e32 v240, v204
	v_mov_b32_e32 v241, v205
	v_mov_b32_e32 v242, v206
	v_mov_b32_e32 v243, v207
	v_mov_b32_e32 v244, v208
	v_mov_b32_e32 v245, v209
	v_mov_b32_e32 v246, v210
	v_mov_b32_e32 v247, v211
	s_mov_b32 s98, 0x5320
	s_mov_b32 s99, 0x6a0
	s_mov_b32 s100, 0x7180
	s_mov_b32 s101, 15
	s_branch .Lcv_hop3
